# v076 + two redundant per-iteration workgroup barriers removed: RG-LRU tile-top S0 (thread-local RAW only) and mLSTM chunk-top B0 for chunks>=1 (kept on the first-chunk entry path)
# baseline (speedup 1.0000x reference)
; #define LAS __attribute__((address_space(3)))
; DI void phase_mlstm(const Params& p, unsigned char* shm, const int vb) {
;     ...
;     for (int unit = vb; unit < 256; unit += gridDim.x) {
;         const int bh = (unit & 7) * 16 + (unit >> 4), half = (unit >> 3) & 1, b = bh >> 2, h = bh & 3;
;         f32x16 C[8];
;         unsigned pf0 = 0u, pf1 = 0u;
; #pragma unroll
;         for (int i = 0; i < 8; ++i)
; #pragma unroll
;             for (int e = 0; e < 16; ++e) C[i][e] = 0.f;
;         if (threadIdx.x < 256) { n_s[threadIdx.x] = 0.f; nacc[threadIdx.x] = 0.f; }
;         { const int tid = threadIdx.x; if (tid < 480) *(LAS u32x4*)(lds + KI + (65 + (tid >> 5)) * RS + 16 * (tid & 31)) = (u32x4){0u, 0u, 0u, 0u}; }
;         for (int c = 0; c < 32; ++c) {
;             __syncthreads();
.LBB0_389:
	s_or_b64 exec, exec, s[2:3]
	s_and_saveexec_b64 s[2:3], s[44:45]
	ds_write_b128 v175, v[160:163] offset:34320
	s_or_b64 exec, exec, s[2:3]
	s_ashr_i32 s64, s27, 4
	s_bfe_u32 s0, s41, 0x30004
	s_and_b32 s3, s64, 3
	s_lshl_b32 s2, s0, 4
	s_lshl_b32 s0, s0, 13
	s_lshl_b32 s65, s3, 8
	s_lshl_b32 s15, s3, 9
	s_add_u32 s36, s94, s15
	s_addc_u32 s37, s95, 0
	s_add_u32 s56, s58, s15
	s_addc_u32 s57, s59, 0
	s_lshl_b32 s3, s3, 10
	s_add_u32 s15, s16, s3
	s_addc_u32 s39, s17, 0
	s_lshl_b32 s46, s27, 6
	s_and_b32 s46, s46, 0x200
	s_add_u32 s66, s15, s46
	s_addc_u32 s67, s39, 0
	v_readlane_b32 s8, v246, 51
	v_readlane_b32 s9, v246, 52
	s_add_u32 s3, s8, s3
	s_addc_u32 s15, s9, 0
	s_add_u32 s70, s3, s46
	s_addc_u32 s71, s15, 0
	s_add_i32 s2, s64, s2
	s_ashr_i32 s3, s2, 31
	s_lshl_b64 s[46:47], s[2:3], 13
	v_readlane_b32 s8, v244, 0
	v_readlane_b32 s9, v244, 1
	s_add_u32 s15, s8, s46
	s_addc_u32 s39, s9, s47
	s_lshl_b64 s[72:73], s[2:3], 11
	s_lshl_b32 s2, s64, 9
	s_add_i32 s0, s0, s2
	s_and_b32 s74, s0, 0xfffff800
	v_mov_b32_e32 v0, 0
	s_ashr_i32 s75, s74, 31
	s_waitcnt vmcnt(4)
	v_mov_b32_e32 v178, 0
	s_mov_b64 s[76:77], 0
	s_lshl_b32 s0, s65, 1
	v_mov_b32_e32 v177, 0
	v_mov_b32_e32 v1, v0
	v_mov_b32_e32 v2, v0
	v_mov_b32_e32 v3, v0
	v_mov_b32_e32 v4, v0
	v_mov_b32_e32 v5, v0
	v_mov_b32_e32 v6, v0
	v_mov_b32_e32 v7, v0
	v_mov_b32_e32 v8, v0
	v_mov_b32_e32 v9, v0
	v_mov_b32_e32 v10, v0
	v_mov_b32_e32 v11, v0
	v_mov_b32_e32 v12, v0
	v_mov_b32_e32 v13, v0
	v_mov_b32_e32 v14, v0
	v_mov_b32_e32 v15, v0
	v_mov_b32_e32 v16, v0
	v_mov_b32_e32 v17, v0
	v_mov_b32_e32 v18, v0
	v_mov_b32_e32 v19, v0
	v_mov_b32_e32 v20, v0
	v_mov_b32_e32 v21, v0
	v_mov_b32_e32 v22, v0
	v_mov_b32_e32 v23, v0
	v_mov_b32_e32 v24, v0
	v_mov_b32_e32 v25, v0
	v_mov_b32_e32 v26, v0
	v_mov_b32_e32 v27, v0
	v_mov_b32_e32 v28, v0
	v_mov_b32_e32 v29, v0
	v_mov_b32_e32 v30, v0
	v_mov_b32_e32 v31, v0
	v_mov_b32_e32 v32, v0
	v_mov_b32_e32 v33, v0
	v_mov_b32_e32 v34, v0
	v_mov_b32_e32 v35, v0
	v_mov_b32_e32 v36, v0
	v_mov_b32_e32 v37, v0
	v_mov_b32_e32 v38, v0
	v_mov_b32_e32 v39, v0
	v_mov_b32_e32 v40, v0
	v_mov_b32_e32 v41, v0
	v_mov_b32_e32 v42, v0
	v_mov_b32_e32 v43, v0
	v_mov_b32_e32 v44, v0
	v_mov_b32_e32 v45, v0
	v_mov_b32_e32 v46, v0
	v_mov_b32_e32 v47, v0
	v_mov_b32_e32 v48, v0
	v_mov_b32_e32 v49, v0
	v_mov_b32_e32 v50, v0
	v_mov_b32_e32 v51, v0
	v_mov_b32_e32 v52, v0
	v_mov_b32_e32 v53, v0
	v_mov_b32_e32 v54, v0
	v_mov_b32_e32 v55, v0
	v_mov_b32_e32 v56, v0
	v_mov_b32_e32 v57, v0
	v_mov_b32_e32 v58, v0
	v_mov_b32_e32 v59, v0
	v_mov_b32_e32 v60, v0
	v_mov_b32_e32 v61, v0
	v_mov_b32_e32 v62, v0
	v_mov_b32_e32 v63, v0
	v_mov_b32_e32 v64, v0
	v_mov_b32_e32 v65, v0
	v_mov_b32_e32 v66, v0
	v_mov_b32_e32 v67, v0
	v_mov_b32_e32 v68, v0
	v_mov_b32_e32 v69, v0
	v_mov_b32_e32 v70, v0
	v_mov_b32_e32 v71, v0
	v_mov_b32_e32 v72, v0
	v_mov_b32_e32 v73, v0
	v_mov_b32_e32 v74, v0
	v_mov_b32_e32 v75, v0
	v_mov_b32_e32 v76, v0
	v_mov_b32_e32 v77, v0
	v_mov_b32_e32 v78, v0
	v_mov_b32_e32 v79, v0
	v_mov_b32_e32 v80, v0
	v_mov_b32_e32 v81, v0
	v_mov_b32_e32 v82, v0
	v_mov_b32_e32 v83, v0
	v_mov_b32_e32 v84, v0
	v_mov_b32_e32 v85, v0
	v_mov_b32_e32 v86, v0
	v_mov_b32_e32 v87, v0
	v_mov_b32_e32 v88, v0
	v_mov_b32_e32 v89, v0
	v_mov_b32_e32 v90, v0
	v_mov_b32_e32 v91, v0
	v_mov_b32_e32 v92, v0
	v_mov_b32_e32 v93, v0
	v_mov_b32_e32 v94, v0
	v_mov_b32_e32 v95, v0
	v_mov_b32_e32 v96, v0
	v_mov_b32_e32 v97, v0
	v_mov_b32_e32 v98, v0
	v_mov_b32_e32 v99, v0
	v_mov_b32_e32 v100, v0
	v_mov_b32_e32 v101, v0
	v_mov_b32_e32 v102, v0
	v_mov_b32_e32 v103, v0
	v_mov_b32_e32 v104, v0
	v_mov_b32_e32 v105, v0
	v_mov_b32_e32 v106, v0
	v_mov_b32_e32 v107, v0
	v_mov_b32_e32 v108, v0
	v_mov_b32_e32 v109, v0
	v_mov_b32_e32 v110, v0
	v_mov_b32_e32 v111, v0
	v_mov_b32_e32 v112, v0
	v_mov_b32_e32 v113, v0
	v_mov_b32_e32 v114, v0
	v_mov_b32_e32 v115, v0
	v_mov_b32_e32 v116, v0
	v_mov_b32_e32 v117, v0
	v_mov_b32_e32 v118, v0
	v_mov_b32_e32 v119, v0
	v_mov_b32_e32 v120, v0
	v_mov_b32_e32 v121, v0
	v_mov_b32_e32 v122, v0
	v_mov_b32_e32 v123, v0
	v_mov_b32_e32 v124, v0
	v_mov_b32_e32 v125, v0
	v_mov_b32_e32 v126, v0
	v_mov_b32_e32 v127, v0
	s_waitcnt lgkmcnt(0)
	s_barrier
	s_branch .LBB0_394

; DI int opq(int x) { asm volatile("" : "+v"(x)); return x; }
; DI void phase_mlstm(const Params& p, unsigned char* shm, const int vb) {
;     ...
;             __syncthreads();
;             asm volatile("" :: "v"(pf0), "v"(pf1));
;             const int t0 = b * S_ + c * 64; const size_t gbase = (size_t)bh * S_ + c * 64;
;             {
;                 const int tid = opq(threadIdx.x), r4 = tid >> 5, cgp = tid & 31;
;                 if (tid < 64) { Pc[tid] = GP[gbase + tid]; Qc[tid] = GQ[gbase + tid]; dec[tid] = GD[gbase + tid]; flr[tid] = GF[gbase + tid]; wls[tid] = GW[gbase + tid]; rsum[tid] = 0.f; }
.LBB0_394:
	s_nop 0
	v_mov_b32_e32 v128, v192
	s_waitcnt lgkmcnt(0)
	s_waitcnt vmcnt(4)
	s_nop 0
	v_cmp_gt_i32_e32 vcc, 64, v128
	s_and_saveexec_b64 s[2:3], vcc
	s_cbranch_execz .LBB0_396
	v_ashrrev_i32_e32 v129, 31, v128
	v_lshl_add_u64 v[130:131], s[72:73], 0, v[128:129]
	v_lshlrev_b64 v[130:131], 2, v[130:131]
	v_lshl_add_u64 v[132:133], s[4:5], 0, v[130:131]
	global_load_dword v129, v[132:133], off
	v_lshl_add_u32 v134, v128, 2, 0
	v_add_u32_e32 v132, 0x1db00, v134
	s_waitcnt vmcnt(0)
	ds_write_b32 v132, v129
	v_lshl_add_u64 v[132:133], s[6:7], 0, v[130:131]
	global_load_dword v129, v[132:133], off
	v_add_u32_e32 v132, 0x1dc00, v134
	s_waitcnt vmcnt(0)
	ds_write_b32 v132, v129
	v_lshl_add_u64 v[132:133], s[48:49], 0, v[130:131]
	global_load_dword v129, v[132:133], off
	v_add_u32_e32 v132, 0x1dd00, v134
	s_waitcnt vmcnt(0)
	ds_write_b32 v132, v129
	v_lshl_add_u64 v[132:133], s[50:51], 0, v[130:131]
	global_load_dword v129, v[132:133], off
	v_add_u32_e32 v132, 0x1de00, v134
	v_lshl_add_u64 v[130:131], s[52:53], 0, v[130:131]
	s_waitcnt vmcnt(0)
	ds_write_b32 v132, v129
	global_load_dword v129, v[130:131], off
	v_add_u32_e32 v130, 0x1df00, v134
	s_waitcnt vmcnt(0)
	ds_write_b32 v130, v129
	v_add_u32_e32 v129, 0x1da00, v134
	ds_write_b32 v129, v169

; #define LAS __attribute__((address_space(3)))
; DI void phase_rglru(const Params& p, unsigned char* shm) {
;     ...
;         for (int tile = 0; tile < 32; ++tile) {
;             __syncthreads();
; #pragma unroll
;             for (int j = 0; j < 3; ++j) { *(LAS u32x4*)(lds + XR + 3 * TR + loff[j]) = rx[j]; *(LAS u32x4*)(lds + GT + loff[j]) = rg[j]; }
;             if (tile < 31) {
;                 const size_t nb = base + (size_t)(tile + 1) * 64 * 1536;
; #pragma unroll
;                 for (int j = 0; j < 3; ++j) { rx[j] = *(const u32x4*)(XRg + nb + goff[j]); rg[j] = *(const u32x4*)(Gg + nb + goff[j]); }
;             }
.LBB0_843:
	s_cmp_eq_u32 s64, 31
	s_mul_i32 s10, s64, 0x18000
	s_waitcnt lgkmcnt(0)
	s_waitcnt vmcnt(5)
	ds_write_b128 v201, v[96:99] offset:1200
	s_waitcnt vmcnt(4)
	ds_write_b128 v201, v[100:103] offset:52480
	s_waitcnt vmcnt(3)
	ds_write_b128 v202, v[104:107] offset:1200
	s_waitcnt vmcnt(2)
	ds_write_b128 v202, v[108:111] offset:52480
	s_waitcnt vmcnt(1)
	ds_write_b128 v203, v[112:115] offset:1200
	s_waitcnt vmcnt(0)
	ds_write_b128 v203, v[116:119] offset:52480
	s_cbranch_scc1 .LBB0_845
	s_add_i32 s2, s10, 0x18000
	s_mov_b32 s3, s11
	s_lshl_b64 s[2:3], s[2:3], 1
	s_add_u32 s28, s0, s2
	s_addc_u32 s29, s1, s3
	s_add_u32 s2, s22, s2
	s_addc_u32 s3, s23, s3
	v_lshl_add_u64 v[96:97], s[28:29], 0, v[164:165]
	v_lshl_add_u64 v[100:101], s[2:3], 0, v[164:165]
	v_lshl_add_u64 v[104:105], s[28:29], 0, v[166:167]
	v_lshl_add_u64 v[108:109], s[2:3], 0, v[166:167]
	v_lshl_add_u64 v[112:113], s[28:29], 0, v[168:169]
	v_lshl_add_u64 v[116:117], s[2:3], 0, v[168:169]
	global_load_dwordx4 v[96:99], v[96:97], off
	s_nop 0
	global_load_dwordx4 v[100:103], v[100:101], off
	s_nop 0
	global_load_dwordx4 v[104:107], v[104:105], off
	s_nop 0
	global_load_dwordx4 v[108:111], v[108:109], off
	s_nop 0
	global_load_dwordx4 v[112:115], v[112:113], off
	s_nop 0
	global_load_dwordx4 v[116:119], v[116:117], off
